# v38 + H1 (first-norm output, in-projection A operand) placed at workspace offset 388 MiB instead of 108 MiB
# speedup vs baseline: 1.0046x; 1.0046x over previous
.LBB0_105:
	s_cmp_ge_i32 s15, s14
	s_cbranch_scc1 .LBB0_113
	v_readlane_b32 s36, v254, 0
	v_mov_b32_e32 v69, 0
	v_lshlrev_b32_e32 v68, 2, v2
	v_readlane_b32 s50, v254, 14
	v_readlane_b32 s51, v254, 15
	v_ashrrev_i32_e32 v67, 31, v66
	s_movk_i32 s0, 0x200
	v_lshl_add_u64 v[70:71], s[50:51], 0, v[68:69]
	v_lshlrev_b32_e32 v68, 2, v2
	v_mbcnt_lo_u32_b32 v2, -1, 0
	v_mbcnt_hi_u32_b32 v78, -1, v2
	v_cmp_gt_u32_e64 s[2:3], s0, v0
	s_add_u32 s8, s74, 0x100000
	v_lshl_add_u64 v[4:5], v[66:67], 3, s[74:75]
	s_mov_b64 s[0:1], 0x18400000
	v_and_b32_e32 v2, 64, v78
	v_lshl_add_u32 v76, v66, 4, 0
	s_addc_u32 s9, s75, 0
	v_lshl_add_u32 v77, v0, 4, 0
	v_lshl_add_u64 v[72:73], v[4:5], 0, s[0:1]
	s_movk_i32 s10, 0x1000
	v_add_u32_e32 v79, 64, v2
	v_xor_b32_e32 v80, 1, v78
	v_xor_b32_e32 v81, 2, v78
	v_xor_b32_e32 v82, 4, v78
	v_xor_b32_e32 v83, 8, v78
	v_xor_b32_e32 v84, 16, v78
	v_xor_b32_e32 v85, 32, v78
	v_mov_b32_e32 v86, 0x358637bd
	s_mov_b32 s11, 0x800000
	s_mov_b64 s[0:1], 0x8000
	v_readlane_b32 s37, v254, 1
	v_readlane_b32 s38, v254, 2
	v_readlane_b32 s39, v254, 3
	v_readlane_b32 s40, v254, 4
	v_readlane_b32 s41, v254, 5
	v_readlane_b32 s42, v254, 6
	v_readlane_b32 s43, v254, 7
	v_readlane_b32 s44, v254, 8
	v_readlane_b32 s45, v254, 9
	v_readlane_b32 s46, v254, 10
	v_readlane_b32 s47, v254, 11
	v_readlane_b32 s48, v254, 12
	v_readlane_b32 s49, v254, 13
	s_branch .LBB0_108

.LBB0_167:
	s_cmp_lt_i32 s76, 3
	s_cselect_b64 s[0:1], -1, 0
	s_cmp_gt_i32 s77, 2
	s_cselect_b64 s[2:3], -1, 0
	s_and_b64 s[0:1], s[0:1], s[2:3]
	s_andn2_b64 vcc, exec, s[0:1]
	s_cbranch_vccnz .LBB0_270
	s_cmpk_gt_i32 s30, 0x68f
	v_readfirstlane_b32 s3, v0
	s_cbranch_scc1 .LBB0_190
	v_lshrrev_b32_e32 v2, 5, v0
	v_lshrrev_b32_e32 v4, 1, v0
	v_and_b32_e32 v2, 4, v2
	v_bfe_u32 v3, v0, 2, 2
	v_and_b32_e32 v13, 24, v4
	s_add_u32 s28, s74, 0x18400000
	v_or3_b32 v2, v2, v3, v13
	v_lshlrev_b32_e32 v3, 4, v0
	s_addc_u32 s29, s75, 0
	v_or_b32_e32 v10, 0x2000, v3
	s_add_u32 s31, s74, 0xc00000
	v_lshrrev_b32_e32 v4, 7, v10
	s_movk_i32 s0, 0x60
	s_addc_u32 s40, s75, 0
	v_and_or_b32 v5, v4, s0, v2
	v_bfe_u32 v14, v0, 2, 4
	s_movk_i32 s0, 0x70
	s_ashr_i32 s42, s30, 31
	v_and_or_b32 v4, v4, s0, v14
	s_lshr_b32 s0, s42, 29
	s_add_i32 s0, s30, s0
	s_lshr_b32 s6, s3, 6
	s_ashr_i32 s1, s0, 3
	s_and_b32 s0, s0, -8
	s_lshr_b32 s8, s3, 8
	s_lshl_b32 s41, s6, 10
	s_sub_i32 s0, s30, s0
	s_cmp_lt_i32 s0, 0
	s_movk_i32 s43, 0xd3
	s_cselect_b32 s2, s43, 0xd2
	s_mul_i32 s0, s0, s2
	s_add_i32 s0, s0, s1
	s_mul_hi_i32 s1, s0, 0x30c30c31
	s_lshr_b32 s2, s1, 31
	s_ashr_i32 s1, s1, 5
	s_add_i32 s1, s1, s2
	s_lshl_b32 s4, s1, 3
	s_mulk_i32 s1, 0xa8
	s_sub_i32 s0, s0, s1
	s_sext_i32_i16 s1, s0
	s_bfe_u32 s1, s1, 0x3001c
	s_add_i32 s1, s0, s1
	s_sext_i32_i16 s2, s1
	s_and_b32 s1, s1, 0xfff8
	s_sub_i32 s0, s0, s1
	s_sext_i32_i16 s0, s0
	v_and_b32_e32 v6, 32, v0
	s_lshr_b32 s2, s2, 3
	s_add_i32 s20, s4, s0
	v_bitop3_b32 v11, v3, v6, 48 bitop3:0x6c
	v_and_b32_e32 v12, 64, v0
	s_ashr_i32 s21, s20, 31
	s_bfe_i64 s[4:5], s[2:3], 0x100000
	v_or_b32_e32 v3, v11, v12
	s_lshl_b64 s[0:1], s[20:21], 20
	s_lshl_b64 s[4:5], s[4:5], 20
	v_lshl_or_b32 v132, v4, 12, v3
	v_lshrrev_b32_e32 v4, 3, v0
	s_add_u32 s24, s31, s4
	v_and_or_b32 v2, v4, 32, v2
	s_addc_u32 s25, s40, s5
	s_add_i32 s46, s41, 0
	v_lshl_or_b32 v134, v2, 12, v3
	s_add_i32 m0, s46, 0x10000
	v_lshl_or_b32 v130, v5, 12, v3
	global_load_lds_dwordx4 v134, s[24:25]
	s_add_i32 m0, s46, 0x12000
	s_add_u32 s4, s24, 0x80000
	global_load_lds_dwordx4 v130, s[24:25]
	s_addc_u32 s5, s25, 0
	s_add_i32 m0, s46, 0x14000
	v_and_or_b32 v2, v4, 48, v14
	global_load_lds_dwordx4 v134, s[4:5]
	s_add_i32 m0, s46, 0x16000
	s_add_u32 s22, s28, s0
	s_addc_u32 s23, s29, s1
	s_add_i32 s47, s46, 0x2000
	v_lshl_or_b32 v136, v2, 12, v3
	global_load_lds_dwordx4 v130, s[4:5]
	s_mov_b32 m0, s46
	s_add_u32 s0, s22, 0x80000
	global_load_lds_dwordx4 v136, s[22:23]
	s_mov_b32 m0, s47
	s_addc_u32 s1, s23, 0
	s_add_i32 s48, s46, 0x4000
	global_load_lds_dwordx4 v132, s[22:23]
	s_mov_b32 m0, s48
	s_add_i32 s49, s46, 0x6000
	global_load_lds_dwordx4 v136, s[0:1]
	s_mov_b32 m0, s49
	v_mov_b32_e32 v135, 0
	global_load_lds_dwordx4 v132, s[0:1]
	v_mov_b32_e32 v131, v135
	v_mov_b32_e32 v137, v135
	v_mov_b32_e32 v133, v135
	s_cmp_eq_u32 s8, 1
	s_mov_b32 s56, 0
	v_lshl_add_u64 v[8:9], s[24:25], 0, v[134:135]
	v_lshl_add_u64 v[6:7], s[24:25], 0, v[130:131]
	v_lshl_add_u64 v[2:3], s[22:23], 0, v[136:137]
	s_cselect_b64 s[0:1], -1, 0
	s_cmp_lg_u32 s8, 1
	v_lshl_add_u64 v[4:5], s[22:23], 0, v[132:133]
	s_cbranch_scc1 .LBB0_171
	s_barrier
